# P6 SwiGLU epilogue: gate*up products of all rows formed while the ss loads are in flight, scale factors reassociated (20 packed ops per row instead of 24)
# speedup vs baseline: 1.0025x; 1.0025x over previous
.LBB0_671:
	ds_read_b128 v[156:159], v151
	ds_read_b128 v[160:163], v151 offset:1024
	ds_read_b128 v[164:167], v151 offset:2048
	ds_read_b128 v[168:171], v151 offset:3072
	ds_read_b128 v[172:175], v152
	ds_read_b128 v[176:179], v152 offset:1024
	ds_read_b128 v[180:183], v152 offset:2048
	ds_read_b128 v[184:187], v152 offset:3072
	s_add_u32 s28, s26, 0xfff80080
	s_addc_u32 s29, s27, -1
	s_cmp_eq_u32 s53, 28
	s_cselect_b32 s31, s19, s29
	s_cselect_b32 s30, s49, s28
	s_cselect_b32 s29, s17, s52
	s_cselect_b32 s28, s50, s51
	s_add_u32 s100, s30, 0x80
	s_addc_u32 s101, s31, 0
	s_add_i32 m0, s25, 0xc000
	ds_read_b128 v[188:191], v153
	ds_read_b128 v[192:195], v153 offset:1024
	ds_read_b128 v[196:199], v153 offset:2048
	ds_read_b128 v[200:203], v153 offset:3072
	ds_read_b128 v[204:207], v153 offset:4096
	ds_read_b128 v[208:211], v153 offset:5120
	ds_read_b128 v[212:215], v153 offset:6144
	ds_read_b128 v[216:219], v153 offset:7168
	global_load_lds_dwordx4 v138, s[26:27]
	s_add_i32 m0, s25, 0xe000
	s_nop 0
	global_load_lds_dwordx4 v140, s[26:27]
	s_waitcnt vmcnt(8)
	s_waitcnt lgkmcnt(0)
	s_barrier
	s_waitcnt lgkmcnt(0)
	v_mfma_f32_16x16x32_bf16 v[116:119], v[156:159], v[188:191], v[116:119]
	v_mfma_f32_16x16x32_bf16 v[116:119], v[160:163], v[192:195], v[116:119]
	v_mfma_f32_16x16x32_bf16 v[112:115], v[164:167], v[188:191], v[112:115]
	v_mfma_f32_16x16x32_bf16 v[112:115], v[168:171], v[192:195], v[112:115]
	v_mfma_f32_16x16x32_bf16 v[96:99], v[164:167], v[196:199], v[96:99]
	v_mfma_f32_16x16x32_bf16 v[96:99], v[168:171], v[200:203], v[96:99]
	v_mfma_f32_16x16x32_bf16 v[100:103], v[156:159], v[196:199], v[100:103]
	v_mfma_f32_16x16x32_bf16 v[100:103], v[160:163], v[200:203], v[100:103]
	v_mfma_f32_16x16x32_bf16 v[84:87], v[156:159], v[204:207], v[84:87]
	v_mfma_f32_16x16x32_bf16 v[84:87], v[160:163], v[208:211], v[84:87]
	v_mfma_f32_16x16x32_bf16 v[80:83], v[164:167], v[204:207], v[80:83]
	v_mfma_f32_16x16x32_bf16 v[80:83], v[168:171], v[208:211], v[80:83]
	v_mfma_f32_16x16x32_bf16 v[64:67], v[164:167], v[212:215], v[64:67]
	v_mfma_f32_16x16x32_bf16 v[64:67], v[168:171], v[216:219], v[64:67]
	v_mfma_f32_16x16x32_bf16 v[68:71], v[156:159], v[212:215], v[68:71]
	v_mfma_f32_16x16x32_bf16 v[68:71], v[160:163], v[216:219], v[68:71]
	v_mfma_f32_16x16x32_bf16 v[124:127], v[172:175], v[188:191], v[124:127]
	v_mfma_f32_16x16x32_bf16 v[124:127], v[176:179], v[192:195], v[124:127]
	v_mfma_f32_16x16x32_bf16 v[120:123], v[180:183], v[188:191], v[120:123]
	v_mfma_f32_16x16x32_bf16 v[120:123], v[184:187], v[192:195], v[120:123]
	v_mfma_f32_16x16x32_bf16 v[104:107], v[180:183], v[196:199], v[104:107]
	v_mfma_f32_16x16x32_bf16 v[104:107], v[184:187], v[200:203], v[104:107]
	v_mfma_f32_16x16x32_bf16 v[108:111], v[172:175], v[196:199], v[108:111]
	v_mfma_f32_16x16x32_bf16 v[108:111], v[176:179], v[200:203], v[108:111]
	v_mfma_f32_16x16x32_bf16 v[92:95], v[172:175], v[204:207], v[92:95]
	v_mfma_f32_16x16x32_bf16 v[92:95], v[176:179], v[208:211], v[92:95]
	v_mfma_f32_16x16x32_bf16 v[88:91], v[180:183], v[204:207], v[88:91]
	v_mfma_f32_16x16x32_bf16 v[88:91], v[184:187], v[208:211], v[88:91]
	v_mfma_f32_16x16x32_bf16 v[72:75], v[180:183], v[212:215], v[72:75]
	v_mfma_f32_16x16x32_bf16 v[72:75], v[184:187], v[216:219], v[72:75]
	v_mfma_f32_16x16x32_bf16 v[76:79], v[172:175], v[212:215], v[76:79]
	v_mfma_f32_16x16x32_bf16 v[76:79], v[176:179], v[216:219], v[76:79]
	s_barrier
	s_add_i32 s54, s46, s36
	s_mov_b32 m0, s54
	ds_read_b128 v[188:191], v153 offset:16384
	ds_read_b128 v[192:195], v153 offset:17408
	ds_read_b128 v[196:199], v153 offset:18432
	ds_read_b128 v[200:203], v153 offset:19456
	ds_read_b128 v[204:207], v153 offset:20480
	ds_read_b128 v[208:211], v153 offset:21504
	ds_read_b128 v[212:215], v153 offset:22528
	ds_read_b128 v[216:219], v153 offset:23552
	global_load_lds_dwordx4 v134, s[28:29]
	s_add_i32 m0, s54, 0x2000
	s_add_u32 s54, s28, 0x80000
	s_addc_u32 s55, s29, 0
	s_add_i32 s56, s47, s36
	global_load_lds_dwordx4 v130, s[28:29]
	s_mov_b32 m0, s56
	s_nop 0
	global_load_lds_dwordx4 v134, s[54:55]
	s_add_i32 m0, s56, 0x2000
	s_nop 0
	global_load_lds_dwordx4 v130, s[54:55]
	s_mov_b32 m0, s25
	s_nop 0
	global_load_lds_dwordx4 v136, s[30:31]
	s_mov_b32 m0, s39
	s_nop 0
	global_load_lds_dwordx4 v132, s[30:31]
	s_waitcnt vmcnt(8)
	s_waitcnt lgkmcnt(0)
	s_barrier
	s_waitcnt lgkmcnt(0)
	v_mfma_f32_16x16x32_bf16 v[52:55], v[156:159], v[188:191], v[52:55]
	v_mfma_f32_16x16x32_bf16 v[52:55], v[160:163], v[192:195], v[52:55]
	v_mfma_f32_16x16x32_bf16 v[48:51], v[164:167], v[188:191], v[48:51]
	v_mfma_f32_16x16x32_bf16 v[48:51], v[168:171], v[192:195], v[48:51]
	v_mfma_f32_16x16x32_bf16 v[32:35], v[164:167], v[196:199], v[32:35]
	v_mfma_f32_16x16x32_bf16 v[32:35], v[168:171], v[200:203], v[32:35]
	v_mfma_f32_16x16x32_bf16 v[36:39], v[156:159], v[196:199], v[36:39]
	v_mfma_f32_16x16x32_bf16 v[36:39], v[160:163], v[200:203], v[36:39]
	v_mfma_f32_16x16x32_bf16 v[20:23], v[156:159], v[204:207], v[20:23]
	v_mfma_f32_16x16x32_bf16 v[20:23], v[160:163], v[208:211], v[20:23]
	v_mfma_f32_16x16x32_bf16 v[16:19], v[164:167], v[204:207], v[16:19]
	v_mfma_f32_16x16x32_bf16 v[16:19], v[168:171], v[208:211], v[16:19]
	v_mfma_f32_16x16x32_bf16 v[0:3], v[164:167], v[212:215], v[0:3]
	v_mfma_f32_16x16x32_bf16 v[0:3], v[168:171], v[216:219], v[0:3]
	v_mfma_f32_16x16x32_bf16 v[8:11], v[156:159], v[212:215], v[8:11]
	v_mfma_f32_16x16x32_bf16 v[8:11], v[160:163], v[216:219], v[8:11]
	v_mfma_f32_16x16x32_bf16 v[60:63], v[172:175], v[188:191], v[60:63]
	v_mfma_f32_16x16x32_bf16 v[60:63], v[176:179], v[192:195], v[60:63]
	v_mfma_f32_16x16x32_bf16 v[56:59], v[180:183], v[188:191], v[56:59]
	v_mfma_f32_16x16x32_bf16 v[56:59], v[184:187], v[192:195], v[56:59]
	v_mfma_f32_16x16x32_bf16 v[40:43], v[180:183], v[196:199], v[40:43]
	v_mfma_f32_16x16x32_bf16 v[40:43], v[184:187], v[200:203], v[40:43]
	v_mfma_f32_16x16x32_bf16 v[44:47], v[172:175], v[196:199], v[44:47]
	v_mfma_f32_16x16x32_bf16 v[44:47], v[176:179], v[200:203], v[44:47]
	v_mfma_f32_16x16x32_bf16 v[28:31], v[172:175], v[204:207], v[28:31]
	v_mfma_f32_16x16x32_bf16 v[28:31], v[176:179], v[208:211], v[28:31]
	v_mfma_f32_16x16x32_bf16 v[24:27], v[180:183], v[204:207], v[24:27]
	v_mfma_f32_16x16x32_bf16 v[24:27], v[184:187], v[208:211], v[24:27]
	v_mfma_f32_16x16x32_bf16 v[4:7], v[180:183], v[212:215], v[4:7]
	v_mfma_f32_16x16x32_bf16 v[4:7], v[184:187], v[216:219], v[4:7]
	v_mfma_f32_16x16x32_bf16 v[12:15], v[172:175], v[212:215], v[12:15]
	v_mfma_f32_16x16x32_bf16 v[12:15], v[176:179], v[216:219], v[12:15]
	s_barrier
	s_add_i32 s54, 0, 0x18000
	v_add_u32_e32 v155, s54, v149
	s_add_i32 s55, 0, 0x1c000
	ds_read_b128 v[156:159], v155
	ds_read_b128 v[160:163], v155 offset:1024
	ds_read_b128 v[164:167], v155 offset:2048
	ds_read_b128 v[168:171], v155 offset:3072
	v_add_u32_e32 v155, s55, v149
	ds_read_b128 v[172:175], v155
	ds_read_b128 v[176:179], v155 offset:1024
	ds_read_b128 v[180:183], v155 offset:2048
	ds_read_b128 v[184:187], v155 offset:3072
	s_add_u32 s30, s30, 0x80000
	s_addc_u32 s31, s31, 0
	s_mov_b32 m0, s40
	ds_read_b128 v[188:191], v153 offset:32768
	ds_read_b128 v[192:195], v153 offset:33792
	ds_read_b128 v[196:199], v153 offset:34816
	ds_read_b128 v[200:203], v153 offset:35840
	ds_read_b128 v[204:207], v153 offset:36864
	ds_read_b128 v[208:211], v153 offset:37888
	ds_read_b128 v[212:215], v153 offset:38912
	ds_read_b128 v[216:219], v153 offset:39936
	global_load_lds_dwordx4 v136, s[30:31]
	s_mov_b32 m0, s41
	s_nop 0
	global_load_lds_dwordx4 v132, s[30:31]
	s_waitcnt vmcnt(8)
	s_waitcnt lgkmcnt(0)
	s_barrier
	s_waitcnt lgkmcnt(0)
	v_mfma_f32_16x16x32_bf16 v[116:119], v[156:159], v[188:191], v[116:119]
	v_mfma_f32_16x16x32_bf16 v[116:119], v[160:163], v[192:195], v[116:119]
	v_mfma_f32_16x16x32_bf16 v[112:115], v[164:167], v[188:191], v[112:115]
	v_mfma_f32_16x16x32_bf16 v[112:115], v[168:171], v[192:195], v[112:115]
	v_mfma_f32_16x16x32_bf16 v[96:99], v[164:167], v[196:199], v[96:99]
	v_mfma_f32_16x16x32_bf16 v[96:99], v[168:171], v[200:203], v[96:99]
	v_mfma_f32_16x16x32_bf16 v[100:103], v[156:159], v[196:199], v[100:103]
	v_mfma_f32_16x16x32_bf16 v[100:103], v[160:163], v[200:203], v[100:103]
	v_mfma_f32_16x16x32_bf16 v[84:87], v[156:159], v[204:207], v[84:87]
	v_mfma_f32_16x16x32_bf16 v[84:87], v[160:163], v[208:211], v[84:87]
	v_mfma_f32_16x16x32_bf16 v[80:83], v[164:167], v[204:207], v[80:83]
	v_mfma_f32_16x16x32_bf16 v[80:83], v[168:171], v[208:211], v[80:83]
	v_mfma_f32_16x16x32_bf16 v[64:67], v[164:167], v[212:215], v[64:67]
	v_mfma_f32_16x16x32_bf16 v[64:67], v[168:171], v[216:219], v[64:67]
	v_mfma_f32_16x16x32_bf16 v[68:71], v[156:159], v[212:215], v[68:71]
	v_mfma_f32_16x16x32_bf16 v[68:71], v[160:163], v[216:219], v[68:71]
	v_mfma_f32_16x16x32_bf16 v[124:127], v[172:175], v[188:191], v[124:127]
	v_mfma_f32_16x16x32_bf16 v[124:127], v[176:179], v[192:195], v[124:127]
	v_mfma_f32_16x16x32_bf16 v[120:123], v[180:183], v[188:191], v[120:123]
	v_mfma_f32_16x16x32_bf16 v[120:123], v[184:187], v[192:195], v[120:123]
	v_mfma_f32_16x16x32_bf16 v[104:107], v[180:183], v[196:199], v[104:107]
	v_mfma_f32_16x16x32_bf16 v[104:107], v[184:187], v[200:203], v[104:107]
	v_mfma_f32_16x16x32_bf16 v[108:111], v[172:175], v[196:199], v[108:111]
	v_mfma_f32_16x16x32_bf16 v[108:111], v[176:179], v[200:203], v[108:111]
	v_mfma_f32_16x16x32_bf16 v[92:95], v[172:175], v[204:207], v[92:95]
	v_mfma_f32_16x16x32_bf16 v[92:95], v[176:179], v[208:211], v[92:95]
	v_mfma_f32_16x16x32_bf16 v[88:91], v[180:183], v[204:207], v[88:91]
	v_mfma_f32_16x16x32_bf16 v[88:91], v[184:187], v[208:211], v[88:91]
	v_mfma_f32_16x16x32_bf16 v[72:75], v[180:183], v[212:215], v[72:75]
	v_mfma_f32_16x16x32_bf16 v[72:75], v[184:187], v[216:219], v[72:75]
	v_mfma_f32_16x16x32_bf16 v[76:79], v[172:175], v[212:215], v[76:79]
	v_mfma_f32_16x16x32_bf16 v[76:79], v[176:179], v[216:219], v[76:79]
	s_barrier
	s_add_i32 s30, s54, s36
	s_add_u32 s98, s28, 0x80
	s_addc_u32 s99, s29, 0
	s_mov_b32 m0, s30
	ds_read_b128 v[188:191], v153 offset:49152
	ds_read_b128 v[192:195], v153 offset:50176
	ds_read_b128 v[196:199], v153 offset:51200
	ds_read_b128 v[200:203], v153 offset:52224
	ds_read_b128 v[204:207], v153 offset:53248
	ds_read_b128 v[208:211], v153 offset:54272
	ds_read_b128 v[212:215], v153 offset:55296
	ds_read_b128 v[216:219], v153 offset:56320
	global_load_lds_dwordx4 v134, s[98:99]
	s_add_i32 m0, s30, 0x2000
	s_add_u32 s28, s28, 0x80080
	s_addc_u32 s29, s29, 0
	s_add_i32 s30, s55, s36
	global_load_lds_dwordx4 v130, s[98:99]
	s_mov_b32 m0, s30
	s_nop 0
	global_load_lds_dwordx4 v134, s[28:29]
	s_add_i32 m0, s30, 0x2000
	s_nop 0
	global_load_lds_dwordx4 v130, s[28:29]
	s_mov_b32 m0, s43
	s_nop 0
	global_load_lds_dwordx4 v136, s[100:101]
	s_mov_b32 m0, s44
	s_nop 0
	global_load_lds_dwordx4 v132, s[100:101]
	s_waitcnt vmcnt(8)
	s_waitcnt lgkmcnt(0)
	s_barrier
	s_waitcnt lgkmcnt(0)
	v_mfma_f32_16x16x32_bf16 v[52:55], v[156:159], v[188:191], v[52:55]
	v_mfma_f32_16x16x32_bf16 v[52:55], v[160:163], v[192:195], v[52:55]
	v_mfma_f32_16x16x32_bf16 v[48:51], v[164:167], v[188:191], v[48:51]
	v_mfma_f32_16x16x32_bf16 v[48:51], v[168:171], v[192:195], v[48:51]
	v_mfma_f32_16x16x32_bf16 v[32:35], v[164:167], v[196:199], v[32:35]
	v_mfma_f32_16x16x32_bf16 v[32:35], v[168:171], v[200:203], v[32:35]
	v_mfma_f32_16x16x32_bf16 v[36:39], v[156:159], v[196:199], v[36:39]
	v_mfma_f32_16x16x32_bf16 v[36:39], v[160:163], v[200:203], v[36:39]
	v_mfma_f32_16x16x32_bf16 v[20:23], v[156:159], v[204:207], v[20:23]
	v_mfma_f32_16x16x32_bf16 v[20:23], v[160:163], v[208:211], v[20:23]
	v_mfma_f32_16x16x32_bf16 v[16:19], v[164:167], v[204:207], v[16:19]
	v_mfma_f32_16x16x32_bf16 v[16:19], v[168:171], v[208:211], v[16:19]
	v_mfma_f32_16x16x32_bf16 v[0:3], v[164:167], v[212:215], v[0:3]
	v_mfma_f32_16x16x32_bf16 v[0:3], v[168:171], v[216:219], v[0:3]
	v_mfma_f32_16x16x32_bf16 v[8:11], v[156:159], v[212:215], v[8:11]
	v_mfma_f32_16x16x32_bf16 v[8:11], v[160:163], v[216:219], v[8:11]
	v_mfma_f32_16x16x32_bf16 v[60:63], v[172:175], v[188:191], v[60:63]
	v_mfma_f32_16x16x32_bf16 v[60:63], v[176:179], v[192:195], v[60:63]
	v_mfma_f32_16x16x32_bf16 v[56:59], v[180:183], v[188:191], v[56:59]
	v_mfma_f32_16x16x32_bf16 v[56:59], v[184:187], v[192:195], v[56:59]
	v_mfma_f32_16x16x32_bf16 v[40:43], v[180:183], v[196:199], v[40:43]
	v_mfma_f32_16x16x32_bf16 v[40:43], v[184:187], v[200:203], v[40:43]
	v_mfma_f32_16x16x32_bf16 v[44:47], v[172:175], v[196:199], v[44:47]
	v_mfma_f32_16x16x32_bf16 v[44:47], v[176:179], v[200:203], v[44:47]
	v_mfma_f32_16x16x32_bf16 v[28:31], v[172:175], v[204:207], v[28:31]
	v_mfma_f32_16x16x32_bf16 v[28:31], v[176:179], v[208:211], v[28:31]
	v_mfma_f32_16x16x32_bf16 v[24:27], v[180:183], v[204:207], v[24:27]
	v_mfma_f32_16x16x32_bf16 v[24:27], v[184:187], v[208:211], v[24:27]
	v_mfma_f32_16x16x32_bf16 v[4:7], v[180:183], v[212:215], v[4:7]
	v_mfma_f32_16x16x32_bf16 v[4:7], v[184:187], v[216:219], v[4:7]
	v_mfma_f32_16x16x32_bf16 v[12:15], v[172:175], v[212:215], v[12:15]
	v_mfma_f32_16x16x32_bf16 v[12:15], v[176:179], v[216:219], v[12:15]
	s_barrier
	s_add_i32 s53, s53, 2
	s_add_u32 s26, s26, 0x100
	s_addc_u32 s27, s27, 0
	s_add_u32 s51, s51, 0x100
	s_addc_u32 s52, s52, 0
	s_cmp_gt_u32 s53, 29
	s_cbranch_scc0 .LBB0_671
	v_lshl_add_u32 v146, s24, 8, v148
	v_lshlrev_b32_e32 v147, 5, v146
	v_add_u32_e32 v254, 0x1000, v147
	global_load_dwordx4 v[156:159], v147, s[10:11]
	global_load_dwordx4 v[160:163], v147, s[10:11] offset:16
	global_load_dwordx4 v[164:167], v147, s[10:11] offset:512
	global_load_dwordx4 v[168:171], v147, s[10:11] offset:528
	global_load_dwordx4 v[172:175], v147, s[10:11] offset:1024
	global_load_dwordx4 v[176:179], v147, s[10:11] offset:1040
	global_load_dwordx4 v[180:183], v147, s[10:11] offset:1536
	global_load_dwordx4 v[184:187], v147, s[10:11] offset:1552
	global_load_dwordx4 v[188:191], v254, s[10:11]
	global_load_dwordx4 v[192:195], v254, s[10:11] offset:16
	global_load_dwordx4 v[196:199], v254, s[10:11] offset:512
	global_load_dwordx4 v[200:203], v254, s[10:11] offset:528
	global_load_dwordx4 v[204:207], v254, s[10:11] offset:1024
	global_load_dwordx4 v[208:211], v254, s[10:11] offset:1040
	global_load_dwordx4 v[212:215], v254, s[10:11] offset:1536
	global_load_dwordx4 v[216:219], v254, s[10:11] offset:1552
	v_mul_u32_u24_e32 v155, 0x2c00, v146
	v_lshl_or_b32 v255, s2, 7, v150
	v_mov_b32_e32 v252, 0xbfb8aa3b
	v_mov_b32_e32 v253, 1.0
	v_lshl_add_u32 v155, v255, 1, v155
	v_pk_mul_f32 v[124:125], v[116:117], v[124:125]
	v_pk_mul_f32 v[126:127], v[118:119], v[126:127]
	v_pk_mul_f32 v[120:121], v[112:113], v[120:121]
	v_pk_mul_f32 v[122:123], v[114:115], v[122:123]
	v_pk_mul_f32 v[108:109], v[100:101], v[108:109]
	v_pk_mul_f32 v[110:111], v[102:103], v[110:111]
	v_pk_mul_f32 v[104:105], v[96:97], v[104:105]
	v_pk_mul_f32 v[106:107], v[98:99], v[106:107]
	v_pk_mul_f32 v[92:93], v[84:85], v[92:93]
	v_pk_mul_f32 v[94:95], v[86:87], v[94:95]
	v_pk_mul_f32 v[88:89], v[80:81], v[88:89]
	v_pk_mul_f32 v[90:91], v[82:83], v[90:91]
	v_pk_mul_f32 v[76:77], v[68:69], v[76:77]
	v_pk_mul_f32 v[78:79], v[70:71], v[78:79]
	v_pk_mul_f32 v[72:73], v[64:65], v[72:73]
	v_pk_mul_f32 v[74:75], v[66:67], v[74:75]
	v_pk_mul_f32 v[60:61], v[52:53], v[60:61]
	v_pk_mul_f32 v[62:63], v[54:55], v[62:63]
	v_pk_mul_f32 v[56:57], v[48:49], v[56:57]
	v_pk_mul_f32 v[58:59], v[50:51], v[58:59]
	v_pk_mul_f32 v[44:45], v[36:37], v[44:45]
	v_pk_mul_f32 v[46:47], v[38:39], v[46:47]
	v_pk_mul_f32 v[40:41], v[32:33], v[40:41]
	v_pk_mul_f32 v[42:43], v[34:35], v[42:43]
	v_pk_mul_f32 v[28:29], v[20:21], v[28:29]
	v_pk_mul_f32 v[30:31], v[22:23], v[30:31]
	v_pk_mul_f32 v[24:25], v[16:17], v[24:25]
	v_pk_mul_f32 v[26:27], v[18:19], v[26:27]
	v_pk_mul_f32 v[12:13], v[8:9], v[12:13]
	v_pk_mul_f32 v[14:15], v[10:11], v[14:15]
	v_pk_mul_f32 v[4:5], v[0:1], v[4:5]
	v_pk_mul_f32 v[6:7], v[2:3], v[6:7]
	s_and_b64 vcc, exec, s[14:15]
	s_cbranch_vccz .LBB0_674
	s_barrier
.LBB0_674:
	s_andn2_b64 vcc, exec, s[0:1]
	s_mov_b64 s[0:1], -1
	s_waitcnt vmcnt(14)
	v_add_f32_e32 v156, v156, v157
	v_add_f32_e32 v158, v158, v159
	v_add_f32_e32 v160, v160, v161
	v_add_f32_e32 v162, v162, v163
	v_add_f32_e32 v156, v156, v158
	v_add_f32_e32 v160, v160, v162
	v_add_f32_e32 v156, v156, v160
	v_fmamk_f32 v156, v156, 0x3a000000, v154
	v_rsq_f32_e32 v146, v156
	v_mov_b32_e32 v147, v155
	v_mul_f32_e32 v254, v146, v146
	v_mul_f32_e32 v255, v146, v252
	v_pk_mul_f32 v[156:157], v[116:117], v[254:255] op_sel:[0,1]
	v_pk_mul_f32 v[158:159], v[118:119], v[254:255] op_sel:[0,1]
	v_pk_mul_f32 v[160:161], v[112:113], v[254:255] op_sel:[0,1]
	v_pk_mul_f32 v[162:163], v[114:115], v[254:255] op_sel:[0,1]
	v_exp_f32_e32 v156, v156
	v_exp_f32_e32 v157, v157
	v_exp_f32_e32 v158, v158
	v_exp_f32_e32 v159, v159
	v_exp_f32_e32 v160, v160
	v_exp_f32_e32 v161, v161
	v_exp_f32_e32 v162, v162
	v_exp_f32_e32 v163, v163
	v_pk_add_f32 v[156:157], v[156:157], v[252:253] op_sel:[0,1]
	v_pk_add_f32 v[158:159], v[158:159], v[252:253] op_sel:[0,1]
	v_pk_add_f32 v[160:161], v[160:161], v[252:253] op_sel:[0,1]
	v_pk_add_f32 v[162:163], v[162:163], v[252:253] op_sel:[0,1]
	v_rcp_f32_e32 v156, v156
	v_rcp_f32_e32 v157, v157
	v_rcp_f32_e32 v158, v158
	v_rcp_f32_e32 v159, v159
	v_rcp_f32_e32 v160, v160
	v_rcp_f32_e32 v161, v161
	v_rcp_f32_e32 v162, v162
	v_rcp_f32_e32 v163, v163
	v_pk_mul_f32 v[124:125], v[124:125], v[156:157]
	v_pk_mul_f32 v[126:127], v[126:127], v[158:159]
	v_pk_mul_f32 v[120:121], v[120:121], v[160:161]
	v_pk_mul_f32 v[122:123], v[122:123], v[162:163]
	v_pk_mul_f32 v[124:125], v[124:125], v[254:255] op_sel_hi:[1,0]
	v_pk_mul_f32 v[126:127], v[126:127], v[254:255] op_sel_hi:[1,0]
	v_pk_mul_f32 v[120:121], v[120:121], v[254:255] op_sel_hi:[1,0]
	v_pk_mul_f32 v[122:123], v[122:123], v[254:255] op_sel_hi:[1,0]
	v_cvt_pk_bf16_f32 v112, v124, v125
	v_cvt_pk_bf16_f32 v113, v126, v127
	v_cvt_pk_bf16_f32 v114, v120, v121
	v_cvt_pk_bf16_f32 v115, v122, v123
	global_store_dwordx4 v147, v[112:115], s[8:9]
	s_waitcnt vmcnt(13)
	v_add_f32_e32 v164, v164, v165
	v_add_f32_e32 v166, v166, v167
	v_add_f32_e32 v168, v168, v169
	v_add_f32_e32 v170, v170, v171
	v_add_f32_e32 v164, v164, v166
	v_add_f32_e32 v168, v168, v170
	v_add_f32_e32 v164, v164, v168
	v_fmamk_f32 v164, v164, 0x3a000000, v154
	v_rsq_f32_e32 v146, v164
	v_add_u32_e32 v147, 0x2c000, v155
	v_mul_f32_e32 v254, v146, v146
	v_mul_f32_e32 v255, v146, v252
	v_pk_mul_f32 v[164:165], v[100:101], v[254:255] op_sel:[0,1]
	v_pk_mul_f32 v[166:167], v[102:103], v[254:255] op_sel:[0,1]
	v_pk_mul_f32 v[168:169], v[96:97], v[254:255] op_sel:[0,1]
	v_pk_mul_f32 v[170:171], v[98:99], v[254:255] op_sel:[0,1]
	v_exp_f32_e32 v164, v164
	v_exp_f32_e32 v165, v165
	v_exp_f32_e32 v166, v166
	v_exp_f32_e32 v167, v167
	v_exp_f32_e32 v168, v168
	v_exp_f32_e32 v169, v169
	v_exp_f32_e32 v170, v170
	v_exp_f32_e32 v171, v171
	v_pk_add_f32 v[164:165], v[164:165], v[252:253] op_sel:[0,1]
	v_pk_add_f32 v[166:167], v[166:167], v[252:253] op_sel:[0,1]
	v_pk_add_f32 v[168:169], v[168:169], v[252:253] op_sel:[0,1]
	v_pk_add_f32 v[170:171], v[170:171], v[252:253] op_sel:[0,1]
	v_rcp_f32_e32 v164, v164
	v_rcp_f32_e32 v165, v165
	v_rcp_f32_e32 v166, v166
	v_rcp_f32_e32 v167, v167
	v_rcp_f32_e32 v168, v168
	v_rcp_f32_e32 v169, v169
	v_rcp_f32_e32 v170, v170
	v_rcp_f32_e32 v171, v171
	v_pk_mul_f32 v[108:109], v[108:109], v[164:165]
	v_pk_mul_f32 v[110:111], v[110:111], v[166:167]
	v_pk_mul_f32 v[104:105], v[104:105], v[168:169]
	v_pk_mul_f32 v[106:107], v[106:107], v[170:171]
	v_pk_mul_f32 v[108:109], v[108:109], v[254:255] op_sel_hi:[1,0]
	v_pk_mul_f32 v[110:111], v[110:111], v[254:255] op_sel_hi:[1,0]
	v_pk_mul_f32 v[104:105], v[104:105], v[254:255] op_sel_hi:[1,0]
	v_pk_mul_f32 v[106:107], v[106:107], v[254:255] op_sel_hi:[1,0]
	v_cvt_pk_bf16_f32 v96, v108, v109
	v_cvt_pk_bf16_f32 v97, v110, v111
	v_cvt_pk_bf16_f32 v98, v104, v105
	v_cvt_pk_bf16_f32 v99, v106, v107
	global_store_dwordx4 v147, v[96:99], s[8:9]
	s_waitcnt vmcnt(12)
	v_add_f32_e32 v172, v172, v173
	v_add_f32_e32 v174, v174, v175
	v_add_f32_e32 v176, v176, v177
	v_add_f32_e32 v178, v178, v179
	v_add_f32_e32 v172, v172, v174
	v_add_f32_e32 v176, v176, v178
	v_add_f32_e32 v172, v172, v176
	v_fmamk_f32 v172, v172, 0x3a000000, v154
	v_rsq_f32_e32 v146, v172
	v_add_u32_e32 v147, 0x58000, v155
	v_mul_f32_e32 v254, v146, v146
	v_mul_f32_e32 v255, v146, v252
	v_pk_mul_f32 v[172:173], v[84:85], v[254:255] op_sel:[0,1]
	v_pk_mul_f32 v[174:175], v[86:87], v[254:255] op_sel:[0,1]
	v_pk_mul_f32 v[176:177], v[80:81], v[254:255] op_sel:[0,1]
	v_pk_mul_f32 v[178:179], v[82:83], v[254:255] op_sel:[0,1]
	v_exp_f32_e32 v172, v172
	v_exp_f32_e32 v173, v173
	v_exp_f32_e32 v174, v174
	v_exp_f32_e32 v175, v175
	v_exp_f32_e32 v176, v176
	v_exp_f32_e32 v177, v177
	v_exp_f32_e32 v178, v178
	v_exp_f32_e32 v179, v179
	v_pk_add_f32 v[172:173], v[172:173], v[252:253] op_sel:[0,1]
	v_pk_add_f32 v[174:175], v[174:175], v[252:253] op_sel:[0,1]
	v_pk_add_f32 v[176:177], v[176:177], v[252:253] op_sel:[0,1]
	v_pk_add_f32 v[178:179], v[178:179], v[252:253] op_sel:[0,1]
	v_rcp_f32_e32 v172, v172
	v_rcp_f32_e32 v173, v173
	v_rcp_f32_e32 v174, v174
	v_rcp_f32_e32 v175, v175
	v_rcp_f32_e32 v176, v176
	v_rcp_f32_e32 v177, v177
	v_rcp_f32_e32 v178, v178
	v_rcp_f32_e32 v179, v179
	v_pk_mul_f32 v[92:93], v[92:93], v[172:173]
	v_pk_mul_f32 v[94:95], v[94:95], v[174:175]
	v_pk_mul_f32 v[88:89], v[88:89], v[176:177]
	v_pk_mul_f32 v[90:91], v[90:91], v[178:179]
	v_pk_mul_f32 v[92:93], v[92:93], v[254:255] op_sel_hi:[1,0]
	v_pk_mul_f32 v[94:95], v[94:95], v[254:255] op_sel_hi:[1,0]
	v_pk_mul_f32 v[88:89], v[88:89], v[254:255] op_sel_hi:[1,0]
	v_pk_mul_f32 v[90:91], v[90:91], v[254:255] op_sel_hi:[1,0]
	v_cvt_pk_bf16_f32 v80, v92, v93
	v_cvt_pk_bf16_f32 v81, v94, v95
	v_cvt_pk_bf16_f32 v82, v88, v89
	v_cvt_pk_bf16_f32 v83, v90, v91
	global_store_dwordx4 v147, v[80:83], s[8:9]
	s_waitcnt vmcnt(11)
	v_add_f32_e32 v180, v180, v181
	v_add_f32_e32 v182, v182, v183
	v_add_f32_e32 v184, v184, v185
	v_add_f32_e32 v186, v186, v187
	v_add_f32_e32 v180, v180, v182
	v_add_f32_e32 v184, v184, v186
	v_add_f32_e32 v180, v180, v184
	v_fmamk_f32 v180, v180, 0x3a000000, v154
	v_rsq_f32_e32 v146, v180
	v_add_u32_e32 v147, 0x84000, v155
	v_mul_f32_e32 v254, v146, v146
	v_mul_f32_e32 v255, v146, v252
	v_pk_mul_f32 v[180:181], v[68:69], v[254:255] op_sel:[0,1]
	v_pk_mul_f32 v[182:183], v[70:71], v[254:255] op_sel:[0,1]
	v_pk_mul_f32 v[184:185], v[64:65], v[254:255] op_sel:[0,1]
	v_pk_mul_f32 v[186:187], v[66:67], v[254:255] op_sel:[0,1]
	v_exp_f32_e32 v180, v180
	v_exp_f32_e32 v181, v181
	v_exp_f32_e32 v182, v182
	v_exp_f32_e32 v183, v183
	v_exp_f32_e32 v184, v184
	v_exp_f32_e32 v185, v185
	v_exp_f32_e32 v186, v186
	v_exp_f32_e32 v187, v187
	v_pk_add_f32 v[180:181], v[180:181], v[252:253] op_sel:[0,1]
	v_pk_add_f32 v[182:183], v[182:183], v[252:253] op_sel:[0,1]
	v_pk_add_f32 v[184:185], v[184:185], v[252:253] op_sel:[0,1]
	v_pk_add_f32 v[186:187], v[186:187], v[252:253] op_sel:[0,1]
	v_rcp_f32_e32 v180, v180
	v_rcp_f32_e32 v181, v181
	v_rcp_f32_e32 v182, v182
	v_rcp_f32_e32 v183, v183
	v_rcp_f32_e32 v184, v184
	v_rcp_f32_e32 v185, v185
	v_rcp_f32_e32 v186, v186
	v_rcp_f32_e32 v187, v187
	v_pk_mul_f32 v[76:77], v[76:77], v[180:181]
	v_pk_mul_f32 v[78:79], v[78:79], v[182:183]
	v_pk_mul_f32 v[72:73], v[72:73], v[184:185]
	v_pk_mul_f32 v[74:75], v[74:75], v[186:187]
	v_pk_mul_f32 v[76:77], v[76:77], v[254:255] op_sel_hi:[1,0]
	v_pk_mul_f32 v[78:79], v[78:79], v[254:255] op_sel_hi:[1,0]
	v_pk_mul_f32 v[72:73], v[72:73], v[254:255] op_sel_hi:[1,0]
	v_pk_mul_f32 v[74:75], v[74:75], v[254:255] op_sel_hi:[1,0]
	v_cvt_pk_bf16_f32 v64, v76, v77
	v_cvt_pk_bf16_f32 v65, v78, v79
	v_cvt_pk_bf16_f32 v66, v72, v73
	v_cvt_pk_bf16_f32 v67, v74, v75
	global_store_dwordx4 v147, v[64:67], s[8:9]
	s_waitcnt vmcnt(10)
	v_add_f32_e32 v188, v188, v189
	v_add_f32_e32 v190, v190, v191
	v_add_f32_e32 v192, v192, v193
	v_add_f32_e32 v194, v194, v195
	v_add_f32_e32 v188, v188, v190
	v_add_f32_e32 v192, v192, v194
	v_add_f32_e32 v188, v188, v192
	v_fmamk_f32 v188, v188, 0x3a000000, v154
	v_rsq_f32_e32 v146, v188
	v_add_u32_e32 v147, 0x160000, v155
	v_mul_f32_e32 v254, v146, v146
	v_mul_f32_e32 v255, v146, v252
	v_pk_mul_f32 v[188:189], v[52:53], v[254:255] op_sel:[0,1]
	v_pk_mul_f32 v[190:191], v[54:55], v[254:255] op_sel:[0,1]
	v_pk_mul_f32 v[192:193], v[48:49], v[254:255] op_sel:[0,1]
	v_pk_mul_f32 v[194:195], v[50:51], v[254:255] op_sel:[0,1]
	v_exp_f32_e32 v188, v188
	v_exp_f32_e32 v189, v189
	v_exp_f32_e32 v190, v190
	v_exp_f32_e32 v191, v191
	v_exp_f32_e32 v192, v192
	v_exp_f32_e32 v193, v193
	v_exp_f32_e32 v194, v194
	v_exp_f32_e32 v195, v195
	v_pk_add_f32 v[188:189], v[188:189], v[252:253] op_sel:[0,1]
	v_pk_add_f32 v[190:191], v[190:191], v[252:253] op_sel:[0,1]
	v_pk_add_f32 v[192:193], v[192:193], v[252:253] op_sel:[0,1]
	v_pk_add_f32 v[194:195], v[194:195], v[252:253] op_sel:[0,1]
	v_rcp_f32_e32 v188, v188
	v_rcp_f32_e32 v189, v189
	v_rcp_f32_e32 v190, v190
	v_rcp_f32_e32 v191, v191
	v_rcp_f32_e32 v192, v192
	v_rcp_f32_e32 v193, v193
	v_rcp_f32_e32 v194, v194
	v_rcp_f32_e32 v195, v195
	v_pk_mul_f32 v[60:61], v[60:61], v[188:189]
	v_pk_mul_f32 v[62:63], v[62:63], v[190:191]
	v_pk_mul_f32 v[56:57], v[56:57], v[192:193]
	v_pk_mul_f32 v[58:59], v[58:59], v[194:195]
	v_pk_mul_f32 v[60:61], v[60:61], v[254:255] op_sel_hi:[1,0]
	v_pk_mul_f32 v[62:63], v[62:63], v[254:255] op_sel_hi:[1,0]
	v_pk_mul_f32 v[56:57], v[56:57], v[254:255] op_sel_hi:[1,0]
	v_pk_mul_f32 v[58:59], v[58:59], v[254:255] op_sel_hi:[1,0]
	v_cvt_pk_bf16_f32 v48, v60, v61
	v_cvt_pk_bf16_f32 v49, v62, v63
	v_cvt_pk_bf16_f32 v50, v56, v57
	v_cvt_pk_bf16_f32 v51, v58, v59
	global_store_dwordx4 v147, v[48:51], s[8:9]
	s_waitcnt vmcnt(9)
	v_add_f32_e32 v196, v196, v197
	v_add_f32_e32 v198, v198, v199
	v_add_f32_e32 v200, v200, v201
	v_add_f32_e32 v202, v202, v203
	v_add_f32_e32 v196, v196, v198
	v_add_f32_e32 v200, v200, v202
	v_add_f32_e32 v196, v196, v200
	v_fmamk_f32 v196, v196, 0x3a000000, v154
	v_rsq_f32_e32 v146, v196
	v_add_u32_e32 v147, 0x18c000, v155
	v_mul_f32_e32 v254, v146, v146
	v_mul_f32_e32 v255, v146, v252
	v_pk_mul_f32 v[196:197], v[36:37], v[254:255] op_sel:[0,1]
	v_pk_mul_f32 v[198:199], v[38:39], v[254:255] op_sel:[0,1]
	v_pk_mul_f32 v[200:201], v[32:33], v[254:255] op_sel:[0,1]
	v_pk_mul_f32 v[202:203], v[34:35], v[254:255] op_sel:[0,1]
	v_exp_f32_e32 v196, v196
	v_exp_f32_e32 v197, v197
	v_exp_f32_e32 v198, v198
	v_exp_f32_e32 v199, v199
	v_exp_f32_e32 v200, v200
	v_exp_f32_e32 v201, v201
	v_exp_f32_e32 v202, v202
	v_exp_f32_e32 v203, v203
	v_pk_add_f32 v[196:197], v[196:197], v[252:253] op_sel:[0,1]
	v_pk_add_f32 v[198:199], v[198:199], v[252:253] op_sel:[0,1]
	v_pk_add_f32 v[200:201], v[200:201], v[252:253] op_sel:[0,1]
	v_pk_add_f32 v[202:203], v[202:203], v[252:253] op_sel:[0,1]
	v_rcp_f32_e32 v196, v196
	v_rcp_f32_e32 v197, v197
	v_rcp_f32_e32 v198, v198
	v_rcp_f32_e32 v199, v199
	v_rcp_f32_e32 v200, v200
	v_rcp_f32_e32 v201, v201
	v_rcp_f32_e32 v202, v202
	v_rcp_f32_e32 v203, v203
	v_pk_mul_f32 v[44:45], v[44:45], v[196:197]
	v_pk_mul_f32 v[46:47], v[46:47], v[198:199]
	v_pk_mul_f32 v[40:41], v[40:41], v[200:201]
	v_pk_mul_f32 v[42:43], v[42:43], v[202:203]
	v_pk_mul_f32 v[44:45], v[44:45], v[254:255] op_sel_hi:[1,0]
	v_pk_mul_f32 v[46:47], v[46:47], v[254:255] op_sel_hi:[1,0]
	v_pk_mul_f32 v[40:41], v[40:41], v[254:255] op_sel_hi:[1,0]
	v_pk_mul_f32 v[42:43], v[42:43], v[254:255] op_sel_hi:[1,0]
	v_cvt_pk_bf16_f32 v32, v44, v45
	v_cvt_pk_bf16_f32 v33, v46, v47
	v_cvt_pk_bf16_f32 v34, v40, v41
	v_cvt_pk_bf16_f32 v35, v42, v43
	global_store_dwordx4 v147, v[32:35], s[8:9]
	s_waitcnt vmcnt(8)
	v_add_f32_e32 v204, v204, v205
	v_add_f32_e32 v206, v206, v207
	v_add_f32_e32 v208, v208, v209
	v_add_f32_e32 v210, v210, v211
	v_add_f32_e32 v204, v204, v206
	v_add_f32_e32 v208, v208, v210
	v_add_f32_e32 v204, v204, v208
	v_fmamk_f32 v204, v204, 0x3a000000, v154
	v_rsq_f32_e32 v146, v204
	v_add_u32_e32 v147, 0x1b8000, v155
	v_mul_f32_e32 v254, v146, v146
	v_mul_f32_e32 v255, v146, v252
	v_pk_mul_f32 v[204:205], v[20:21], v[254:255] op_sel:[0,1]
	v_pk_mul_f32 v[206:207], v[22:23], v[254:255] op_sel:[0,1]
	v_pk_mul_f32 v[208:209], v[16:17], v[254:255] op_sel:[0,1]
	v_pk_mul_f32 v[210:211], v[18:19], v[254:255] op_sel:[0,1]
	v_exp_f32_e32 v204, v204
	v_exp_f32_e32 v205, v205
	v_exp_f32_e32 v206, v206
	v_exp_f32_e32 v207, v207
	v_exp_f32_e32 v208, v208
	v_exp_f32_e32 v209, v209
	v_exp_f32_e32 v210, v210
	v_exp_f32_e32 v211, v211
	v_pk_add_f32 v[204:205], v[204:205], v[252:253] op_sel:[0,1]
	v_pk_add_f32 v[206:207], v[206:207], v[252:253] op_sel:[0,1]
	v_pk_add_f32 v[208:209], v[208:209], v[252:253] op_sel:[0,1]
	v_pk_add_f32 v[210:211], v[210:211], v[252:253] op_sel:[0,1]
	v_rcp_f32_e32 v204, v204
	v_rcp_f32_e32 v205, v205
	v_rcp_f32_e32 v206, v206
	v_rcp_f32_e32 v207, v207
	v_rcp_f32_e32 v208, v208
	v_rcp_f32_e32 v209, v209
	v_rcp_f32_e32 v210, v210
	v_rcp_f32_e32 v211, v211
	v_pk_mul_f32 v[28:29], v[28:29], v[204:205]
	v_pk_mul_f32 v[30:31], v[30:31], v[206:207]
	v_pk_mul_f32 v[24:25], v[24:25], v[208:209]
	v_pk_mul_f32 v[26:27], v[26:27], v[210:211]
	v_pk_mul_f32 v[28:29], v[28:29], v[254:255] op_sel_hi:[1,0]
	v_pk_mul_f32 v[30:31], v[30:31], v[254:255] op_sel_hi:[1,0]
	v_pk_mul_f32 v[24:25], v[24:25], v[254:255] op_sel_hi:[1,0]
	v_pk_mul_f32 v[26:27], v[26:27], v[254:255] op_sel_hi:[1,0]
	v_cvt_pk_bf16_f32 v16, v28, v29
	v_cvt_pk_bf16_f32 v17, v30, v31
	v_cvt_pk_bf16_f32 v18, v24, v25
	v_cvt_pk_bf16_f32 v19, v26, v27
	global_store_dwordx4 v147, v[16:19], s[8:9]
	s_waitcnt vmcnt(7)
	v_add_f32_e32 v212, v212, v213
	v_add_f32_e32 v214, v214, v215
	v_add_f32_e32 v216, v216, v217
	v_add_f32_e32 v218, v218, v219
	v_add_f32_e32 v212, v212, v214
	v_add_f32_e32 v216, v216, v218
	v_add_f32_e32 v212, v212, v216
	v_fmamk_f32 v212, v212, 0x3a000000, v154
	v_rsq_f32_e32 v146, v212
	v_add_u32_e32 v147, 0x1e4000, v155
	v_mul_f32_e32 v254, v146, v146
	v_mul_f32_e32 v255, v146, v252
	v_pk_mul_f32 v[212:213], v[8:9], v[254:255] op_sel:[0,1]
	v_pk_mul_f32 v[214:215], v[10:11], v[254:255] op_sel:[0,1]
	v_pk_mul_f32 v[216:217], v[0:1], v[254:255] op_sel:[0,1]
	v_pk_mul_f32 v[218:219], v[2:3], v[254:255] op_sel:[0,1]
	v_exp_f32_e32 v212, v212
	v_exp_f32_e32 v213, v213
	v_exp_f32_e32 v214, v214
	v_exp_f32_e32 v215, v215
	v_exp_f32_e32 v216, v216
	v_exp_f32_e32 v217, v217
	v_exp_f32_e32 v218, v218
	v_exp_f32_e32 v219, v219
	v_pk_add_f32 v[212:213], v[212:213], v[252:253] op_sel:[0,1]
	v_pk_add_f32 v[214:215], v[214:215], v[252:253] op_sel:[0,1]
	v_pk_add_f32 v[216:217], v[216:217], v[252:253] op_sel:[0,1]
	v_pk_add_f32 v[218:219], v[218:219], v[252:253] op_sel:[0,1]
	v_rcp_f32_e32 v212, v212
	v_rcp_f32_e32 v213, v213
	v_rcp_f32_e32 v214, v214
	v_rcp_f32_e32 v215, v215
	v_rcp_f32_e32 v216, v216
	v_rcp_f32_e32 v217, v217
	v_rcp_f32_e32 v218, v218
	v_rcp_f32_e32 v219, v219
	v_pk_mul_f32 v[12:13], v[12:13], v[212:213]
	v_pk_mul_f32 v[14:15], v[14:15], v[214:215]
	v_pk_mul_f32 v[4:5], v[4:5], v[216:217]
	v_pk_mul_f32 v[6:7], v[6:7], v[218:219]
	v_pk_mul_f32 v[12:13], v[12:13], v[254:255] op_sel_hi:[1,0]
	v_pk_mul_f32 v[14:15], v[14:15], v[254:255] op_sel_hi:[1,0]
	v_pk_mul_f32 v[4:5], v[4:5], v[254:255] op_sel_hi:[1,0]
	v_pk_mul_f32 v[6:7], v[6:7], v[254:255] op_sel_hi:[1,0]
	v_cvt_pk_bf16_f32 v0, v12, v13
	v_cvt_pk_bf16_f32 v1, v14, v15
	v_cvt_pk_bf16_f32 v2, v4, v5
	v_cvt_pk_bf16_f32 v3, v6, v7
	global_store_dwordx4 v147, v[0:3], s[8:9]
	s_cbranch_vccnz .LBB0_667
	s_andn2_b64 vcc, exec, s[6:7]
	s_cbranch_vccnz .LBB0_666
	s_barrier
	s_branch .LBB0_666
